# prompt attention K staging counted waits; sample-row unit residual epilogue loads batched
# speedup vs baseline: 1.0298x; 1.0012x over previous
.LBB0_46:
	s_lshl_b32 s1, s16, 5
	s_and_b32 s0, s16, 0x100
	s_and_b32 s1, s1, 0xe0
	s_or_b32 s0, s1, s0
	s_bfe_u32 s1, s16, 0x50003
	s_or_b32 s4, s0, s1
	s_and_b64 s[0:1], s[84:85], exec
	s_cselect_b32 s17, s4, s16
	s_waitcnt lgkmcnt(0)
	v_mov_b32_e32 v129, v214
	s_ashr_i32 s23, s17, 6
	s_bfe_u32 s25, s17, 0x20004
	s_lshl_b32 s17, s17, 7
	s_add_i32 s4, s23, s19
	s_lshl_b32 s23, s23, 11
	s_and_b32 s17, s17, 0x780
	v_ashrrev_i32_e32 v0, 2, v129
	v_bfi_b32 v0, -16, v0, v129
	s_or_b32 s17, s23, s17
	s_ashr_i32 s5, s4, 31
	v_add_u32_e32 v0, s17, v0
	s_mov_b64 s[26:27], s[42:43]
	v_ashrrev_i32_e32 v1, 31, v0
	s_lshl_b64 s[4:5], s[4:5], 19
	s_lshl_b32 s17, s25, 17
	s_mov_b64 s[0:1], s[42:43]
	s_mov_b64 s[28:29], s[42:43]
	v_lshlrev_b64 v[140:141], 11, v[0:1]
	s_lshl_b32 s82, s25, 9
	s_or_b32 s4, s4, s17
	v_bfe_u32 v174, v129, 4, 2
	s_add_u32 s26, s26, s4
	v_lshl_add_u64 v[0:1], s[28:29], 0, v[140:141]
	v_lshlrev_b32_e32 v34, 3, v129
	v_lshlrev_b32_e32 v32, 4, v129
	v_lshl_add_u64 v[0:1], v[0:1], 0, s[82:83]
	v_lshlrev_b32_e32 v102, 4, v174
	v_mov_b32_e32 v103, v193
	s_addc_u32 s27, s27, s5
	v_and_b32_e32 v80, 0x1f0, v32
	v_mov_b32_e32 v81, v193
	v_and_b32_e32 v122, 0xffffff00, v34
	v_lshl_add_u64 v[0:1], v[0:1], 0, v[102:103]
	s_mov_b64 s[28:29], 0xfc00000
	v_lshl_add_u64 v[32:33], s[26:27], 0, v[80:81]
	s_mov_b64 s[26:27], 0x6400000
	v_ashrrev_i32_e32 v123, 31, v122
	v_lshl_add_u64 v[2:3], v[0:1], 0, s[28:29]
	v_add_co_u32_e32 v0, vcc, s31, v0
	v_lshl_add_u64 v[120:121], v[32:33], 0, s[26:27]
	v_lshlrev_b64 v[82:83], 1, v[122:123]
	v_addc_co_u32_e32 v1, vcc, 0, v1, vcc
	v_lshl_add_u64 v[32:33], v[120:121], 0, v[82:83]
	global_load_dwordx4 v[24:27], v[2:3], off offset:64
	global_load_dwordx4 v[20:23], v[2:3], off offset:128
	global_load_dwordx4 v[16:19], v[2:3], off offset:192
	global_load_dwordx4 v[12:15], v[2:3], off offset:256
	global_load_dwordx4 v[8:11], v[2:3], off offset:320
	global_load_dwordx4 v[4:7], v[2:3], off offset:384
	global_load_dwordx4 v[28:31], v[0:1], off
	s_nop 0
	global_load_dwordx4 v[0:3], v[2:3], off offset:448
	v_add_u32_e32 v36, 0x1000, v122
	global_load_dwordx4 v[32:35], v[32:33], off
	v_add_u32_e32 v40, 0x2000, v122
	v_add_u32_e32 v44, 0x3000, v122
	v_add_u32_e32 v48, 0x4000, v122
	v_add_u32_e32 v52, 0x5000, v122
	v_add_u32_e32 v56, 0x6000, v122
	v_add_u32_e32 v60, 0x7000, v122
	v_add_u32_e32 v64, 0x8000, v122
	v_add_u32_e32 v68, 0x9000, v122
	v_add_u32_e32 v72, 0xa000, v122
	v_add_u32_e32 v76, 0xb000, v122
	v_add_u32_e32 v98, 0xc000, v122
	v_ashrrev_i32_e32 v37, 31, v36
	v_ashrrev_i32_e32 v41, 31, v40
	v_ashrrev_i32_e32 v45, 31, v44
	v_ashrrev_i32_e32 v49, 31, v48
	v_ashrrev_i32_e32 v53, 31, v52
	v_ashrrev_i32_e32 v57, 31, v56
	v_ashrrev_i32_e32 v61, 31, v60
	v_ashrrev_i32_e32 v65, 31, v64
	v_ashrrev_i32_e32 v69, 31, v68
	v_ashrrev_i32_e32 v73, 31, v72
	v_ashrrev_i32_e32 v77, 31, v76
	v_ashrrev_i32_e32 v99, 31, v98
	v_add_u32_e32 v108, 0xd000, v122
	v_add_u32_e32 v116, 0xe000, v122
	v_add_u32_e32 v122, 0xf000, v122
	v_lshlrev_b64 v[84:85], 1, v[36:37]
	v_lshlrev_b64 v[86:87], 1, v[40:41]
	v_lshlrev_b64 v[88:89], 1, v[44:45]
	v_lshlrev_b64 v[90:91], 1, v[48:49]
	v_lshlrev_b64 v[92:93], 1, v[52:53]
	v_lshlrev_b64 v[94:95], 1, v[56:57]
	v_lshlrev_b64 v[96:97], 1, v[60:61]
	v_lshlrev_b64 v[104:105], 1, v[64:65]
	v_lshlrev_b64 v[106:107], 1, v[68:69]
	v_lshlrev_b64 v[112:113], 1, v[72:73]
	v_lshlrev_b64 v[114:115], 1, v[76:77]
	v_lshlrev_b64 v[124:125], 1, v[98:99]
	v_ashrrev_i32_e32 v109, 31, v108
	v_ashrrev_i32_e32 v117, 31, v116
	v_ashrrev_i32_e32 v123, 31, v122
	v_lshl_add_u64 v[36:37], v[120:121], 0, v[84:85]
	v_lshl_add_u64 v[40:41], v[120:121], 0, v[86:87]
	v_lshl_add_u64 v[44:45], v[120:121], 0, v[88:89]
	v_lshl_add_u64 v[48:49], v[120:121], 0, v[90:91]
	v_lshl_add_u64 v[52:53], v[120:121], 0, v[92:93]
	v_lshl_add_u64 v[56:57], v[120:121], 0, v[94:95]
	v_lshl_add_u64 v[60:61], v[120:121], 0, v[96:97]
	v_lshl_add_u64 v[64:65], v[120:121], 0, v[104:105]
	v_lshl_add_u64 v[68:69], v[120:121], 0, v[106:107]
	v_lshl_add_u64 v[72:73], v[120:121], 0, v[112:113]
	v_lshl_add_u64 v[76:77], v[120:121], 0, v[114:115]
	v_lshl_add_u64 v[98:99], v[120:121], 0, v[124:125]
	v_lshlrev_b64 v[126:127], 1, v[108:109]
	v_lshlrev_b64 v[132:133], 1, v[116:117]
	v_lshlrev_b64 v[134:135], 1, v[122:123]
	global_load_dwordx4 v[36:39], v[36:37], off
	v_lshl_add_u64 v[108:109], v[120:121], 0, v[126:127]
	global_load_dwordx4 v[40:43], v[40:41], off
	v_lshl_add_u64 v[116:117], v[120:121], 0, v[132:133]
	global_load_dwordx4 v[44:47], v[44:45], off
	v_lshl_add_u64 v[120:121], v[120:121], 0, v[134:135]
	global_load_dwordx4 v[48:51], v[48:49], off
	v_add_u32_e32 v128, 0, v80
	global_load_dwordx4 v[52:55], v[52:53], off
	v_ashrrev_i32_e32 v103, 5, v129
	global_load_dwordx4 v[56:59], v[56:57], off
	v_mad_u64_u32 v[142:143], s[26:27], v103, s34, v[128:129]
	global_load_dwordx4 v[60:63], v[60:61], off
	v_and_b32_e32 v130, 15, v129
	global_load_dwordx4 v[64:67], v[64:65], off
	v_mul_u32_u24_e32 v143, 0x210, v130
	global_load_dwordx4 v[68:71], v[68:69], off
	s_add_u32 s0, s0, s4
	global_load_dwordx4 v[72:75], v[72:73], off
	s_addc_u32 s1, s1, s5
	global_load_dwordx4 v[76:79], v[76:77], off
	v_cmp_lt_i32_e32 vcc, v223, v218
	global_load_dwordx4 v[98:101], v[98:99], off
	v_lshlrev_b32_e32 v192, 3, v174
	global_load_dwordx4 v[108:111], v[108:109], off
	s_nop 0
	global_load_dwordx4 v[116:119], v[116:117], off
	s_nop 0
	global_load_dwordx4 v[120:123], v[120:121], off
	s_waitcnt lgkmcnt(0)
	s_waitcnt vmcnt(15)
	ds_write_b128 v142, v[32:35]
	v_add_u32_e32 v32, 0x200, v129
	v_ashrrev_i32_e32 v32, 5, v32
	v_mad_u64_u32 v[144:145], s[26:27], v32, s34, v[128:129]
	v_add_u32_e32 v32, 0x400, v129
	v_ashrrev_i32_e32 v32, 5, v32
	v_mad_u64_u32 v[146:147], s[26:27], v32, s34, v[128:129]
	v_add_u32_e32 v32, 0x600, v129
	v_ashrrev_i32_e32 v32, 5, v32
	v_mad_u64_u32 v[148:149], s[26:27], v32, s34, v[128:129]
	v_add_u32_e32 v32, 0x800, v129
	v_ashrrev_i32_e32 v32, 5, v32
	v_mad_u64_u32 v[150:151], s[26:27], v32, s34, v[128:129]
	v_add_u32_e32 v32, 0xa00, v129
	v_ashrrev_i32_e32 v32, 5, v32
	v_mad_u64_u32 v[152:153], s[26:27], v32, s34, v[128:129]
	v_add_u32_e32 v32, 0xc00, v129
	v_ashrrev_i32_e32 v32, 5, v32
	v_mad_u64_u32 v[154:155], s[26:27], v32, s34, v[128:129]
	v_add_u32_e32 v32, 0xe00, v129
	v_ashrrev_i32_e32 v32, 5, v32
	v_mad_u64_u32 v[156:157], s[26:27], v32, s34, v[128:129]
	v_add_u32_e32 v32, 0x1000, v129
	v_ashrrev_i32_e32 v32, 5, v32
	v_mad_u64_u32 v[158:159], s[26:27], v32, s34, v[128:129]
	v_add_u32_e32 v32, 0x1200, v129
	v_ashrrev_i32_e32 v32, 5, v32
	v_mad_u64_u32 v[160:161], s[26:27], v32, s34, v[128:129]
	v_add_u32_e32 v32, 0x1400, v129
	v_ashrrev_i32_e32 v32, 5, v32
	v_mad_u64_u32 v[162:163], s[26:27], v32, s34, v[128:129]
	v_add_u32_e32 v32, 0x1600, v129
	v_ashrrev_i32_e32 v32, 5, v32
	v_mad_u64_u32 v[164:165], s[26:27], v32, s34, v[128:129]
	v_add_u32_e32 v32, 0x1800, v129
	v_ashrrev_i32_e32 v32, 5, v32
	v_mad_u64_u32 v[166:167], s[26:27], v32, s34, v[128:129]
	v_add_u32_e32 v32, 0x1a00, v129
	v_ashrrev_i32_e32 v32, 5, v32
	v_mad_u64_u32 v[168:169], s[26:27], v32, s34, v[128:129]
	v_add_u32_e32 v32, 0x1c00, v129
	v_ashrrev_i32_e32 v32, 5, v32
	v_mad_u64_u32 v[170:171], s[26:27], v32, s34, v[128:129]
	v_add_u32_e32 v32, 0x1e00, v129
	v_ashrrev_i32_e32 v32, 5, v32
	s_waitcnt vmcnt(14)
	ds_write_b128 v144, v[36:39]
	s_waitcnt vmcnt(13)
	ds_write_b128 v146, v[40:43]
	s_waitcnt vmcnt(12)
	ds_write_b128 v148, v[44:47]
	s_waitcnt vmcnt(11)
	ds_write_b128 v150, v[48:51]
	s_waitcnt vmcnt(10)
	ds_write_b128 v152, v[52:55]
	s_waitcnt vmcnt(9)
	ds_write_b128 v154, v[56:59]
	s_waitcnt vmcnt(8)
	ds_write_b128 v156, v[60:63]
	s_waitcnt vmcnt(7)
	ds_write_b128 v158, v[64:67]
	s_waitcnt vmcnt(6)
	ds_write_b128 v160, v[68:71]
	v_mad_u64_u32 v[172:173], s[26:27], v32, s34, v[128:129]
	s_waitcnt vmcnt(5)
	ds_write_b128 v162, v[72:75]
	s_waitcnt vmcnt(4)
	ds_write_b128 v164, v[76:79]
	s_waitcnt vmcnt(3)
	ds_write_b128 v166, v[98:101]
	v_add3_u32 v98, 0, v143, v102
	s_waitcnt vmcnt(2)
	ds_write_b128 v168, v[108:111]
	v_add_u32_e32 v99, 0x10800, v98
	s_waitcnt vmcnt(1)
	ds_write_b128 v170, v[116:119]
	v_add_u32_e32 v108, 0x12900, v98
	s_waitcnt vmcnt(0)
	ds_write_b128 v172, v[120:123]
	s_waitcnt lgkmcnt(0)
	s_barrier
	ds_read_b128 v[32:35], v98
	ds_read_b128 v[36:39], v98 offset:64
	ds_read_b128 v[40:43], v98 offset:8448
	ds_read_b128 v[44:47], v98 offset:8512
	s_waitcnt lgkmcnt(3)
	v_mfma_f32_16x16x32_bf16 v[32:35], v[32:35], v[28:31], 0
	v_add_u32_e32 v120, 0x16b00, v98
	v_add_u32_e32 v136, 0x1ad00, v98
	s_waitcnt lgkmcnt(1)
	v_mfma_f32_16x16x32_bf16 v[40:43], v[40:43], v[28:31], 0
	v_mfma_f32_16x16x32_bf16 v[32:35], v[36:39], v[24:27], v[32:35]
	s_waitcnt lgkmcnt(0)
	v_mfma_f32_16x16x32_bf16 v[36:39], v[44:47], v[24:27], v[40:43]
	s_nop 4
	ds_read_b128 v[40:43], v98 offset:128
	ds_read_b128 v[44:47], v98 offset:192
	s_waitcnt lgkmcnt(1)
	v_mfma_f32_16x16x32_bf16 v[32:35], v[40:43], v[20:23], v[32:35]
	ds_read_b128 v[40:43], v98 offset:8576
	ds_read_b128 v[48:51], v98 offset:8640
	s_waitcnt lgkmcnt(1)
	v_mfma_f32_16x16x32_bf16 v[36:39], v[40:43], v[20:23], v[36:39]
	v_mfma_f32_16x16x32_bf16 v[32:35], v[44:47], v[16:19], v[32:35]
	ds_read_b128 v[40:43], v98 offset:256
	ds_read_b128 v[44:47], v98 offset:320
	s_waitcnt lgkmcnt(2)
	v_mfma_f32_16x16x32_bf16 v[36:39], v[48:51], v[16:19], v[36:39]
	s_waitcnt lgkmcnt(1)
	v_mfma_f32_16x16x32_bf16 v[32:35], v[40:43], v[12:15], v[32:35]
	ds_read_b128 v[40:43], v98 offset:8704
	ds_read_b128 v[48:51], v98 offset:8768
	s_waitcnt lgkmcnt(1)
	v_mfma_f32_16x16x32_bf16 v[36:39], v[40:43], v[12:15], v[36:39]
	v_mfma_f32_16x16x32_bf16 v[32:35], v[44:47], v[8:11], v[32:35]
	ds_read_b128 v[40:43], v98 offset:384
	ds_read_b128 v[44:47], v98 offset:448
	s_waitcnt lgkmcnt(2)
	v_mfma_f32_16x16x32_bf16 v[36:39], v[48:51], v[8:11], v[36:39]
	s_waitcnt lgkmcnt(1)
	v_mfma_f32_16x16x32_bf16 v[32:35], v[40:43], v[4:7], v[32:35]
	ds_read_b128 v[40:43], v98 offset:8832
	ds_read_b128 v[48:51], v98 offset:8896
	s_waitcnt lgkmcnt(1)
	v_mfma_f32_16x16x32_bf16 v[40:43], v[40:43], v[4:7], v[36:39]
	v_mfma_f32_16x16x32_bf16 v[36:39], v[44:47], v[0:3], v[32:35]
	s_waitcnt lgkmcnt(0)
	v_mfma_f32_16x16x32_bf16 v[32:35], v[48:51], v[0:3], v[40:43]
	s_nop 4
	ds_read_b128 v[40:43], v98 offset:16896
	ds_read_b128 v[44:47], v98 offset:16960
	ds_read_b128 v[48:51], v98 offset:25344
	ds_read_b128 v[52:55], v98 offset:25408
	s_waitcnt lgkmcnt(3)
	v_mfma_f32_16x16x32_bf16 v[40:43], v[40:43], v[28:31], 0
	s_waitcnt lgkmcnt(1)
	v_mfma_f32_16x16x32_bf16 v[48:51], v[48:51], v[28:31], 0
	v_mfma_f32_16x16x32_bf16 v[40:43], v[44:47], v[24:27], v[40:43]
	s_waitcnt lgkmcnt(0)
	v_mfma_f32_16x16x32_bf16 v[44:47], v[52:55], v[24:27], v[48:51]
	s_nop 4
	ds_read_b128 v[48:51], v98 offset:17024
	ds_read_b128 v[52:55], v98 offset:17088
	s_waitcnt lgkmcnt(1)
	v_mfma_f32_16x16x32_bf16 v[40:43], v[48:51], v[20:23], v[40:43]
	ds_read_b128 v[48:51], v98 offset:25472
	ds_read_b128 v[56:59], v98 offset:25536
	s_waitcnt lgkmcnt(1)
	v_mfma_f32_16x16x32_bf16 v[44:47], v[48:51], v[20:23], v[44:47]
	v_mfma_f32_16x16x32_bf16 v[40:43], v[52:55], v[16:19], v[40:43]
	ds_read_b128 v[48:51], v98 offset:17152
	ds_read_b128 v[52:55], v98 offset:17216
	s_waitcnt lgkmcnt(2)
	v_mfma_f32_16x16x32_bf16 v[44:47], v[56:59], v[16:19], v[44:47]
	s_waitcnt lgkmcnt(1)
	v_mfma_f32_16x16x32_bf16 v[40:43], v[48:51], v[12:15], v[40:43]
	ds_read_b128 v[48:51], v98 offset:25600
	ds_read_b128 v[56:59], v98 offset:25664
	s_waitcnt lgkmcnt(1)
	v_mfma_f32_16x16x32_bf16 v[44:47], v[48:51], v[12:15], v[44:47]
	v_mfma_f32_16x16x32_bf16 v[40:43], v[52:55], v[8:11], v[40:43]
	ds_read_b128 v[48:51], v98 offset:17280
	ds_read_b128 v[52:55], v98 offset:17344
	s_waitcnt lgkmcnt(2)
	v_mfma_f32_16x16x32_bf16 v[44:47], v[56:59], v[8:11], v[44:47]
	s_waitcnt lgkmcnt(1)
	v_mfma_f32_16x16x32_bf16 v[40:43], v[48:51], v[4:7], v[40:43]
	ds_read_b128 v[48:51], v98 offset:25728
	ds_read_b128 v[56:59], v98 offset:25792
	s_waitcnt lgkmcnt(1)
	v_mfma_f32_16x16x32_bf16 v[48:51], v[48:51], v[4:7], v[44:47]
	v_mfma_f32_16x16x32_bf16 v[44:47], v[52:55], v[0:3], v[40:43]
	s_waitcnt lgkmcnt(0)
	v_mfma_f32_16x16x32_bf16 v[40:43], v[56:59], v[0:3], v[48:51]
	s_nop 4
	ds_read_b128 v[48:51], v98 offset:33792
	ds_read_b128 v[52:55], v98 offset:33856
	ds_read_b128 v[56:59], v98 offset:42240
	ds_read_b128 v[60:63], v98 offset:42304
	s_waitcnt lgkmcnt(3)
	v_mfma_f32_16x16x32_bf16 v[48:51], v[48:51], v[28:31], 0
	s_waitcnt lgkmcnt(1)
	v_mfma_f32_16x16x32_bf16 v[56:59], v[56:59], v[28:31], 0
	v_mfma_f32_16x16x32_bf16 v[48:51], v[52:55], v[24:27], v[48:51]
	s_waitcnt lgkmcnt(0)
	v_mfma_f32_16x16x32_bf16 v[52:55], v[60:63], v[24:27], v[56:59]
	s_nop 4
	ds_read_b128 v[56:59], v98 offset:33920
	ds_read_b128 v[60:63], v98 offset:33984
	s_waitcnt lgkmcnt(1)
	v_mfma_f32_16x16x32_bf16 v[48:51], v[56:59], v[20:23], v[48:51]
	ds_read_b128 v[56:59], v98 offset:42368
	ds_read_b128 v[64:67], v98 offset:42432
	s_waitcnt lgkmcnt(1)
	v_mfma_f32_16x16x32_bf16 v[52:55], v[56:59], v[20:23], v[52:55]
	v_mfma_f32_16x16x32_bf16 v[48:51], v[60:63], v[16:19], v[48:51]
	ds_read_b128 v[56:59], v98 offset:34048
	ds_read_b128 v[60:63], v98 offset:34112
	s_waitcnt lgkmcnt(2)
	v_mfma_f32_16x16x32_bf16 v[52:55], v[64:67], v[16:19], v[52:55]
	s_waitcnt lgkmcnt(1)
	v_mfma_f32_16x16x32_bf16 v[48:51], v[56:59], v[12:15], v[48:51]
	ds_read_b128 v[56:59], v98 offset:42496
	ds_read_b128 v[64:67], v98 offset:42560
	s_waitcnt lgkmcnt(1)
	v_mfma_f32_16x16x32_bf16 v[52:55], v[56:59], v[12:15], v[52:55]
	v_mfma_f32_16x16x32_bf16 v[48:51], v[60:63], v[8:11], v[48:51]
	ds_read_b128 v[56:59], v98 offset:34176
	ds_read_b128 v[60:63], v98 offset:34240
	s_waitcnt lgkmcnt(2)
	v_mfma_f32_16x16x32_bf16 v[52:55], v[64:67], v[8:11], v[52:55]
	s_waitcnt lgkmcnt(1)
	v_mfma_f32_16x16x32_bf16 v[48:51], v[56:59], v[4:7], v[48:51]
	ds_read_b128 v[56:59], v98 offset:42624
	ds_read_b128 v[64:67], v98 offset:42688
	s_waitcnt lgkmcnt(1)
	v_mfma_f32_16x16x32_bf16 v[56:59], v[56:59], v[4:7], v[52:55]
	v_mfma_f32_16x16x32_bf16 v[52:55], v[60:63], v[0:3], v[48:51]
	s_waitcnt lgkmcnt(0)
	v_mfma_f32_16x16x32_bf16 v[48:51], v[64:67], v[0:3], v[56:59]
	s_nop 4
	ds_read_b128 v[56:59], v98 offset:50688
	ds_read_b128 v[60:63], v98 offset:50752
	ds_read_b128 v[64:67], v98 offset:59136
	ds_read_b128 v[68:71], v98 offset:59200
	s_waitcnt lgkmcnt(3)
	v_mfma_f32_16x16x32_bf16 v[56:59], v[56:59], v[28:31], 0
	s_waitcnt lgkmcnt(1)
	v_mfma_f32_16x16x32_bf16 v[64:67], v[64:67], v[28:31], 0
	v_mfma_f32_16x16x32_bf16 v[56:59], v[60:63], v[24:27], v[56:59]
	s_waitcnt lgkmcnt(0)
	v_mfma_f32_16x16x32_bf16 v[60:63], v[68:71], v[24:27], v[64:67]
	s_nop 4
	ds_read_b128 v[64:67], v98 offset:50816
	ds_read_b128 v[68:71], v98 offset:50880
	s_waitcnt lgkmcnt(1)
	v_mfma_f32_16x16x32_bf16 v[56:59], v[64:67], v[20:23], v[56:59]
	ds_read_b128 v[64:67], v98 offset:59264
	ds_read_b128 v[72:75], v98 offset:59328
	s_waitcnt lgkmcnt(1)
	v_mfma_f32_16x16x32_bf16 v[60:63], v[64:67], v[20:23], v[60:63]
	v_mfma_f32_16x16x32_bf16 v[56:59], v[68:71], v[16:19], v[56:59]
	ds_read_b128 v[64:67], v98 offset:50944
	ds_read_b128 v[68:71], v98 offset:51008
	s_waitcnt lgkmcnt(2)
	v_mfma_f32_16x16x32_bf16 v[60:63], v[72:75], v[16:19], v[60:63]
	s_waitcnt lgkmcnt(1)
	v_mfma_f32_16x16x32_bf16 v[56:59], v[64:67], v[12:15], v[56:59]
	ds_read_b128 v[64:67], v98 offset:59392
	ds_read_b128 v[72:75], v98 offset:59456
	s_waitcnt lgkmcnt(1)
	v_mfma_f32_16x16x32_bf16 v[60:63], v[64:67], v[12:15], v[60:63]
	v_mfma_f32_16x16x32_bf16 v[56:59], v[68:71], v[8:11], v[56:59]
	ds_read_b128 v[64:67], v98 offset:51072
	ds_read_b128 v[68:71], v98 offset:51136
	s_waitcnt lgkmcnt(2)
	v_mfma_f32_16x16x32_bf16 v[60:63], v[72:75], v[8:11], v[60:63]
	s_waitcnt lgkmcnt(1)
	v_mfma_f32_16x16x32_bf16 v[56:59], v[64:67], v[4:7], v[56:59]
	ds_read_b128 v[64:67], v98 offset:59520
	ds_read_b128 v[72:75], v98 offset:59584
	s_waitcnt lgkmcnt(1)
	v_mfma_f32_16x16x32_bf16 v[64:67], v[64:67], v[4:7], v[60:63]
	v_mfma_f32_16x16x32_bf16 v[60:63], v[68:71], v[0:3], v[56:59]
	ds_read_b128 v[68:71], v99 offset:64
	s_waitcnt lgkmcnt(1)
	v_mfma_f32_16x16x32_bf16 v[56:59], v[72:75], v[0:3], v[64:67]
	s_nop 3
	ds_read_b128 v[64:67], v99
	ds_read_b128 v[72:75], v108
	ds_read_b128 v[76:79], v108 offset:64
	s_waitcnt lgkmcnt(2)
	v_mfma_f32_16x16x32_bf16 v[64:67], v[64:67], v[28:31], 0
	s_waitcnt lgkmcnt(1)
	v_mfma_f32_16x16x32_bf16 v[72:75], v[72:75], v[28:31], 0
	v_mfma_f32_16x16x32_bf16 v[64:67], v[68:71], v[24:27], v[64:67]
	s_waitcnt lgkmcnt(0)
	v_mfma_f32_16x16x32_bf16 v[68:71], v[76:79], v[24:27], v[72:75]
	s_nop 4
	ds_read_b128 v[72:75], v99 offset:128
	ds_read_b128 v[76:79], v99 offset:192
	s_waitcnt lgkmcnt(1)
	v_mfma_f32_16x16x32_bf16 v[64:67], v[72:75], v[20:23], v[64:67]
	ds_read_b128 v[72:75], v108 offset:128
	ds_read_b128 v[100:103], v108 offset:192
	s_waitcnt lgkmcnt(1)
	v_mfma_f32_16x16x32_bf16 v[68:71], v[72:75], v[20:23], v[68:71]
	v_mfma_f32_16x16x32_bf16 v[64:67], v[76:79], v[16:19], v[64:67]
	ds_read_b128 v[72:75], v99 offset:256
	ds_read_b128 v[76:79], v99 offset:320
	s_waitcnt lgkmcnt(2)
	v_mfma_f32_16x16x32_bf16 v[68:71], v[100:103], v[16:19], v[68:71]
	s_waitcnt lgkmcnt(1)
	v_mfma_f32_16x16x32_bf16 v[64:67], v[72:75], v[12:15], v[64:67]
	ds_read_b128 v[72:75], v108 offset:256
	ds_read_b128 v[100:103], v108 offset:320
	s_waitcnt lgkmcnt(1)
	v_mfma_f32_16x16x32_bf16 v[68:71], v[72:75], v[12:15], v[68:71]
	v_mfma_f32_16x16x32_bf16 v[64:67], v[76:79], v[8:11], v[64:67]
	ds_read_b128 v[72:75], v99 offset:384
	ds_read_b128 v[76:79], v99 offset:448
	v_add_u32_e32 v99, 0x14a00, v98
	s_waitcnt lgkmcnt(2)
	v_mfma_f32_16x16x32_bf16 v[68:71], v[100:103], v[8:11], v[68:71]
	s_waitcnt lgkmcnt(1)
	v_mfma_f32_16x16x32_bf16 v[64:67], v[72:75], v[4:7], v[64:67]
	ds_read_b128 v[72:75], v108 offset:384
	ds_read_b128 v[100:103], v108 offset:448
	s_waitcnt lgkmcnt(1)
	v_mfma_f32_16x16x32_bf16 v[72:75], v[72:75], v[4:7], v[68:71]
	v_mfma_f32_16x16x32_bf16 v[68:71], v[76:79], v[0:3], v[64:67]
	ds_read_b128 v[76:79], v99 offset:64
	s_waitcnt lgkmcnt(1)
	v_mfma_f32_16x16x32_bf16 v[64:67], v[100:103], v[0:3], v[72:75]
	s_nop 3
	ds_read_b128 v[72:75], v99
	ds_read_b128 v[100:103], v120
	ds_read_b128 v[108:111], v120 offset:64
	s_waitcnt lgkmcnt(2)
	v_mfma_f32_16x16x32_bf16 v[72:75], v[72:75], v[28:31], 0
	s_waitcnt lgkmcnt(1)
	v_mfma_f32_16x16x32_bf16 v[100:103], v[100:103], v[28:31], 0
	v_mfma_f32_16x16x32_bf16 v[72:75], v[76:79], v[24:27], v[72:75]
	s_waitcnt lgkmcnt(0)
	v_mfma_f32_16x16x32_bf16 v[76:79], v[108:111], v[24:27], v[100:103]
	s_nop 4
	ds_read_b128 v[100:103], v99 offset:128
	ds_read_b128 v[108:111], v99 offset:192
	s_waitcnt lgkmcnt(1)
	v_mfma_f32_16x16x32_bf16 v[72:75], v[100:103], v[20:23], v[72:75]
	ds_read_b128 v[100:103], v120 offset:128
	ds_read_b128 v[116:119], v120 offset:192
	s_waitcnt lgkmcnt(1)
	v_mfma_f32_16x16x32_bf16 v[76:79], v[100:103], v[20:23], v[76:79]
	v_mfma_f32_16x16x32_bf16 v[72:75], v[108:111], v[16:19], v[72:75]
	ds_read_b128 v[100:103], v99 offset:256
	ds_read_b128 v[108:111], v99 offset:320
	s_waitcnt lgkmcnt(2)
	v_mfma_f32_16x16x32_bf16 v[76:79], v[116:119], v[16:19], v[76:79]
	s_waitcnt lgkmcnt(1)
	v_mfma_f32_16x16x32_bf16 v[72:75], v[100:103], v[12:15], v[72:75]
	ds_read_b128 v[100:103], v120 offset:256
	ds_read_b128 v[116:119], v120 offset:320
	s_waitcnt lgkmcnt(1)
	v_mfma_f32_16x16x32_bf16 v[76:79], v[100:103], v[12:15], v[76:79]
	v_mfma_f32_16x16x32_bf16 v[72:75], v[108:111], v[8:11], v[72:75]
	ds_read_b128 v[100:103], v99 offset:384
	ds_read_b128 v[108:111], v99 offset:448
	v_add_u32_e32 v99, 0x18c00, v98
	s_waitcnt lgkmcnt(2)
	v_mfma_f32_16x16x32_bf16 v[76:79], v[116:119], v[8:11], v[76:79]
	s_waitcnt lgkmcnt(1)
	v_mfma_f32_16x16x32_bf16 v[72:75], v[100:103], v[4:7], v[72:75]
	ds_read_b128 v[100:103], v120 offset:384
	ds_read_b128 v[116:119], v120 offset:448
	s_waitcnt lgkmcnt(1)
	v_mfma_f32_16x16x32_bf16 v[100:103], v[100:103], v[4:7], v[76:79]
	v_mfma_f32_16x16x32_bf16 v[76:79], v[108:111], v[0:3], v[72:75]
	ds_read_b128 v[108:111], v99 offset:64
	s_waitcnt lgkmcnt(1)
	v_mfma_f32_16x16x32_bf16 v[72:75], v[116:119], v[0:3], v[100:103]
	s_nop 3
	ds_read_b128 v[100:103], v99
	ds_read_b128 v[116:119], v136
	ds_read_b128 v[120:123], v136 offset:64
	s_waitcnt lgkmcnt(2)
	v_mfma_f32_16x16x32_bf16 v[100:103], v[100:103], v[28:31], 0
	s_waitcnt lgkmcnt(1)
	v_mfma_f32_16x16x32_bf16 v[116:119], v[116:119], v[28:31], 0
	v_mfma_f32_16x16x32_bf16 v[100:103], v[108:111], v[24:27], v[100:103]
	s_waitcnt lgkmcnt(0)
	v_mfma_f32_16x16x32_bf16 v[108:111], v[120:123], v[24:27], v[116:119]
	s_nop 4
	ds_read_b128 v[116:119], v99 offset:128
	ds_read_b128 v[120:123], v99 offset:192
	s_waitcnt lgkmcnt(1)
	v_mfma_f32_16x16x32_bf16 v[100:103], v[116:119], v[20:23], v[100:103]
	ds_read_b128 v[116:119], v136 offset:128
	ds_read_b128 v[128:131], v136 offset:192
	s_waitcnt lgkmcnt(1)
	v_mfma_f32_16x16x32_bf16 v[108:111], v[116:119], v[20:23], v[108:111]
	v_mfma_f32_16x16x32_bf16 v[100:103], v[120:123], v[16:19], v[100:103]
	ds_read_b128 v[116:119], v99 offset:256
	ds_read_b128 v[120:123], v99 offset:320
	s_waitcnt lgkmcnt(2)
	v_mfma_f32_16x16x32_bf16 v[108:111], v[128:131], v[16:19], v[108:111]
	s_waitcnt lgkmcnt(1)
	v_mfma_f32_16x16x32_bf16 v[100:103], v[116:119], v[12:15], v[100:103]
	ds_read_b128 v[116:119], v136 offset:256
	ds_read_b128 v[128:131], v136 offset:320
	s_waitcnt lgkmcnt(1)
	v_mfma_f32_16x16x32_bf16 v[108:111], v[116:119], v[12:15], v[108:111]
	v_mfma_f32_16x16x32_bf16 v[100:103], v[120:123], v[8:11], v[100:103]
	ds_read_b128 v[116:119], v99 offset:384
	ds_read_b128 v[120:123], v99 offset:448
	v_add_u32_e32 v99, 0x1ce00, v98
	v_add_u32_e32 v98, 0x1ef00, v98
	s_waitcnt lgkmcnt(2)
	v_mfma_f32_16x16x32_bf16 v[108:111], v[128:131], v[8:11], v[108:111]
	s_waitcnt lgkmcnt(1)
	v_mfma_f32_16x16x32_bf16 v[100:103], v[116:119], v[4:7], v[100:103]
	ds_read_b128 v[116:119], v136 offset:384
	ds_read_b128 v[128:131], v136 offset:448
	s_waitcnt lgkmcnt(1)
	v_mfma_f32_16x16x32_bf16 v[108:111], v[116:119], v[4:7], v[108:111]
	ds_read_b128 v[116:119], v99 offset:64
	v_mfma_f32_16x16x32_bf16 v[120:123], v[120:123], v[0:3], v[100:103]
	s_waitcnt lgkmcnt(1)
	v_mfma_f32_16x16x32_bf16 v[100:103], v[128:131], v[0:3], v[108:111]
	s_nop 3
	ds_read_b128 v[108:111], v99
	ds_read_b128 v[128:131], v98
	ds_read_b128 v[136:139], v98 offset:64
	s_waitcnt lgkmcnt(2)
	v_mfma_f32_16x16x32_bf16 v[108:111], v[108:111], v[28:31], 0
	s_waitcnt lgkmcnt(1)
	v_mfma_f32_16x16x32_bf16 v[28:31], v[128:131], v[28:31], 0
	v_mfma_f32_16x16x32_bf16 v[108:111], v[116:119], v[24:27], v[108:111]
	s_waitcnt lgkmcnt(0)
	v_mfma_f32_16x16x32_bf16 v[24:27], v[136:139], v[24:27], v[28:31]
	s_nop 4
	ds_read_b128 v[28:31], v99 offset:128
	ds_read_b128 v[116:119], v99 offset:192
	s_waitcnt lgkmcnt(1)
	v_mfma_f32_16x16x32_bf16 v[28:31], v[28:31], v[20:23], v[108:111]
	s_nop 2
	ds_read_b128 v[108:111], v98 offset:128
	ds_read_b128 v[128:131], v98 offset:192
	s_waitcnt lgkmcnt(1)
	v_mfma_f32_16x16x32_bf16 v[20:23], v[108:111], v[20:23], v[24:27]
	v_mfma_f32_16x16x32_bf16 v[24:27], v[116:119], v[16:19], v[28:31]
	s_nop 2
	ds_read_b128 v[28:31], v99 offset:256
	s_waitcnt lgkmcnt(1)
	v_mfma_f32_16x16x32_bf16 v[16:19], v[128:131], v[16:19], v[20:23]
	s_nop 2
	ds_read_b128 v[20:23], v98 offset:256
	ds_read_b128 v[108:111], v99 offset:320
	ds_read_b128 v[116:119], v98 offset:320
	s_waitcnt lgkmcnt(3)
	v_mfma_f32_16x16x32_bf16 v[24:27], v[28:31], v[12:15], v[24:27]
	ds_read_b128 v[28:31], v99 offset:384
	ds_read_b128 v[128:131], v99 offset:448
	ds_read_b128 v[136:139], v98 offset:384
	ds_read_b128 v[176:179], v98 offset:448
	s_waitcnt lgkmcnt(6)
	v_mfma_f32_16x16x32_bf16 v[12:15], v[20:23], v[12:15], v[16:19]
	s_waitcnt lgkmcnt(5)
	v_mfma_f32_16x16x32_bf16 v[24:27], v[108:111], v[8:11], v[24:27]
	s_nop 0
	v_lshl_add_u64 v[16:17], s[0:1], 0, v[80:81]
	s_mov_b64 s[0:1], 0x6c00000
	v_lshl_add_u64 v[180:181], v[16:17], 0, s[0:1]
	s_waitcnt lgkmcnt(4)
	v_mfma_f32_16x16x32_bf16 v[8:11], v[116:119], v[8:11], v[12:15]
	v_lshl_add_u64 v[16:17], v[180:181], 0, v[82:83]
	v_lshl_add_u64 v[20:21], v[180:181], 0, v[84:85]
	v_lshl_add_u64 v[80:81], v[180:181], 0, v[86:87]
	s_waitcnt lgkmcnt(3)
	v_mfma_f32_16x16x32_bf16 v[12:15], v[28:31], v[4:7], v[24:27]
	v_lshl_add_u64 v[82:83], v[180:181], 0, v[88:89]
	global_load_dwordx4 v[16:19], v[16:17], off
	s_nop 0
	global_load_dwordx4 v[20:23], v[20:21], off
	v_lshl_add_u64 v[24:25], v[180:181], 0, v[90:91]
	s_waitcnt lgkmcnt(0)
	v_mfma_f32_16x16x32_bf16 v[8:11], v[136:139], v[4:7], v[8:11]
	global_load_dwordx4 v[28:31], v[80:81], off
	s_nop 0
	global_load_dwordx4 v[80:83], v[82:83], off
	v_lshl_add_u64 v[26:27], v[180:181], 0, v[92:93]
	global_load_dwordx4 v[84:87], v[24:25], off
	global_load_dwordx4 v[88:91], v[26:27], off
	v_lshl_add_u64 v[24:25], v[180:181], 0, v[94:95]
	v_mfma_f32_16x16x32_bf16 v[4:7], v[128:131], v[0:3], v[12:15]
	v_lshl_add_u64 v[26:27], v[180:181], 0, v[96:97]
	global_load_dwordx4 v[92:95], v[24:25], off
	global_load_dwordx4 v[96:99], v[26:27], off
	v_lshl_add_u64 v[12:13], v[180:181], 0, v[104:105]
	v_mfma_f32_16x16x32_bf16 v[0:3], v[176:179], v[0:3], v[8:11]
	s_mov_b64 s[0:1], s[42:43]
	s_nop 1
	v_lshl_add_u64 v[8:9], v[180:181], 0, v[106:107]
	global_load_dwordx4 v[104:107], v[12:13], off
	global_load_dwordx4 v[108:111], v[8:9], off
	v_lshl_add_u64 v[8:9], v[180:181], 0, v[112:113]
	v_lshl_add_u64 v[10:11], v[180:181], 0, v[114:115]
	global_load_dwordx4 v[112:115], v[8:9], off
	global_load_dwordx4 v[116:119], v[10:11], off
	v_max_f32_e32 v8, v38, v38
	v_max_f32_e32 v9, v37, v37
	v_max_f32_e32 v8, v9, v8
	v_max3_f32 v8, v36, s33, v8
	v_max_f32_e32 v9, v34, v34
	v_max_f32_e32 v10, v33, v33
	v_max3_f32 v8, v8, v39, v32
	v_max_f32_e32 v9, v10, v9
	v_max3_f32 v8, v8, v9, v35
	v_max_f32_e32 v9, v46, v46
	v_max_f32_e32 v10, v45, v45
	v_max_f32_e32 v9, v10, v9
	v_max3_f32 v8, v8, v44, v9
	v_max_f32_e32 v9, v42, v42
	v_max_f32_e32 v10, v41, v41
	v_max3_f32 v8, v8, v47, v40
	v_max_f32_e32 v9, v10, v9
	v_max3_f32 v8, v8, v9, v43
	v_max_f32_e32 v9, v54, v54
	v_max_f32_e32 v10, v53, v53
	v_max_f32_e32 v9, v10, v9
	v_max3_f32 v8, v8, v52, v9
	v_max_f32_e32 v9, v50, v50
	v_max_f32_e32 v10, v49, v49
	v_max3_f32 v8, v8, v55, v48
	v_max_f32_e32 v9, v10, v9
	v_max3_f32 v8, v8, v9, v51
	v_max_f32_e32 v9, v62, v62
	v_max_f32_e32 v10, v61, v61
	v_max_f32_e32 v9, v10, v9
	v_max3_f32 v8, v8, v60, v9
	v_max_f32_e32 v9, v58, v58
	v_max_f32_e32 v10, v57, v57
	v_max3_f32 v8, v8, v63, v56
	v_max_f32_e32 v9, v10, v9
	v_max3_f32 v8, v8, v9, v59
	v_max_f32_e32 v9, v70, v70
	v_max_f32_e32 v10, v69, v69
	v_max_f32_e32 v9, v10, v9
	v_max3_f32 v8, v8, v68, v9
	v_max_f32_e32 v9, v66, v66
	v_max_f32_e32 v10, v65, v65
	v_max3_f32 v8, v8, v71, v64
	v_max_f32_e32 v9, v10, v9
	v_max3_f32 v8, v8, v9, v67
	v_max_f32_e32 v9, v78, v78
	v_max_f32_e32 v10, v77, v77
	v_max_f32_e32 v9, v10, v9
	v_max3_f32 v8, v8, v76, v9
	v_max_f32_e32 v9, v74, v74
	v_max_f32_e32 v10, v73, v73
	v_max3_f32 v8, v8, v79, v72
	v_max_f32_e32 v9, v10, v9
	v_max3_f32 v8, v8, v9, v75
	v_max_f32_e32 v9, v122, v122
	v_max_f32_e32 v10, v121, v121
	v_max_f32_e32 v9, v10, v9
	v_max3_f32 v8, v8, v120, v9
	v_max_f32_e32 v9, v102, v102
	v_max_f32_e32 v10, v101, v101
	v_max3_f32 v8, v8, v123, v100
	v_max_f32_e32 v9, v10, v9
	v_max3_f32 v8, v8, v9, v103
	v_max_f32_e32 v9, v6, v6
	v_max_f32_e32 v10, v5, v5
	v_max_f32_e32 v9, v10, v9
	v_max3_f32 v8, v8, v4, v9
	v_max_f32_e32 v9, v2, v2
	v_max_f32_e32 v10, v1, v1
	v_max3_f32 v8, v8, v7, v0
	v_max_f32_e32 v9, v10, v9
	v_max3_f32 v12, v8, v9, v3
	v_cndmask_b32_e32 v8, v217, v223, vcc
	v_lshlrev_b32_e32 v13, 2, v8
	ds_bpermute_b32 v14, v13, v12
	v_lshl_add_u64 v[8:9], v[180:181], 0, v[124:125]
	v_lshl_add_u64 v[10:11], v[180:181], 0, v[126:127]
	global_load_dwordx4 v[124:127], v[8:9], off
	global_load_dwordx4 v[128:131], v[10:11], off
	v_cmp_lt_i32_e32 vcc, v224, v218
	s_waitcnt lgkmcnt(0)
	v_max_f32_e32 v8, v14, v14
	v_max_f32_e32 v12, v12, v8
	v_cndmask_b32_e32 v8, v217, v224, vcc
	v_lshlrev_b32_e32 v14, 2, v8
	ds_bpermute_b32 v15, v14, v12
	v_lshl_add_u64 v[8:9], v[180:181], 0, v[132:133]
	v_lshl_add_u64 v[10:11], v[180:181], 0, v[134:135]
	global_load_dwordx4 v[132:135], v[8:9], off
	global_load_dwordx4 v[136:139], v[10:11], off
	s_waitcnt lgkmcnt(0)
	v_max_f32_e32 v8, v15, v15
	v_max_f32_e32 v8, v12, v8
	v_sub_f32_e32 v9, v36, v8
	v_exp_f32_e32 v9, v9
	v_sub_f32_e32 v10, v37, v8
	v_exp_f32_e32 v10, v10
	v_sub_f32_e32 v11, v38, v8
	v_exp_f32_e32 v11, v11
	v_sub_f32_e32 v12, v39, v8
	v_exp_f32_e32 v12, v12
	v_sub_f32_e32 v24, v32, v8
	v_add_f32_e32 v15, 0, v9
	v_exp_f32_e32 v24, v24
	v_sub_f32_e32 v25, v33, v8
	v_add_f32_e32 v15, v10, v15
	v_exp_f32_e32 v25, v25
	v_sub_f32_e32 v26, v34, v8
	v_add_f32_e32 v15, v11, v15
	v_exp_f32_e32 v26, v26
	v_sub_f32_e32 v27, v35, v8
	v_add_f32_e32 v15, v12, v15
	v_exp_f32_e32 v27, v27
	v_sub_f32_e32 v32, v44, v8
	v_add_f32_e32 v15, v24, v15
	v_exp_f32_e32 v32, v32
	v_sub_f32_e32 v33, v45, v8
	v_add_f32_e32 v15, v25, v15
	v_exp_f32_e32 v33, v33
	v_sub_f32_e32 v34, v46, v8
	v_add_f32_e32 v15, v26, v15
	v_exp_f32_e32 v34, v34
	v_sub_f32_e32 v35, v47, v8
	v_add_f32_e32 v15, v27, v15
	v_exp_f32_e32 v35, v35
	v_sub_f32_e32 v36, v40, v8
	v_add_f32_e32 v15, v32, v15
	v_exp_f32_e32 v36, v36
	v_sub_f32_e32 v37, v41, v8
	v_add_f32_e32 v15, v33, v15
	v_exp_f32_e32 v37, v37
	v_sub_f32_e32 v38, v42, v8
	v_add_f32_e32 v15, v34, v15
	v_exp_f32_e32 v38, v38
	v_sub_f32_e32 v39, v43, v8
	v_add_f32_e32 v15, v35, v15
	v_exp_f32_e32 v39, v39
	v_sub_f32_e32 v40, v52, v8
	v_add_f32_e32 v15, v36, v15
	v_exp_f32_e32 v40, v40
	v_sub_f32_e32 v41, v53, v8
	v_add_f32_e32 v15, v37, v15
	v_exp_f32_e32 v41, v41
	v_sub_f32_e32 v42, v54, v8
	v_add_f32_e32 v15, v38, v15
	v_exp_f32_e32 v42, v42
	v_sub_f32_e32 v43, v55, v8
	v_add_f32_e32 v15, v39, v15
	v_exp_f32_e32 v43, v43
	v_sub_f32_e32 v44, v48, v8
	v_add_f32_e32 v15, v40, v15
	v_exp_f32_e32 v44, v44
	v_sub_f32_e32 v45, v49, v8
	v_add_f32_e32 v15, v41, v15
	v_exp_f32_e32 v45, v45
	v_sub_f32_e32 v46, v50, v8
	v_add_f32_e32 v15, v42, v15
	v_exp_f32_e32 v46, v46
	v_sub_f32_e32 v47, v51, v8
	v_add_f32_e32 v15, v43, v15
	v_exp_f32_e32 v47, v47
	v_sub_f32_e32 v48, v60, v8
	v_add_f32_e32 v15, v44, v15
	v_exp_f32_e32 v48, v48
	v_sub_f32_e32 v49, v61, v8
	v_add_f32_e32 v15, v45, v15
	v_exp_f32_e32 v49, v49
	v_sub_f32_e32 v50, v62, v8
	v_add_f32_e32 v15, v46, v15
	v_exp_f32_e32 v50, v50
	v_sub_f32_e32 v51, v63, v8
	v_add_f32_e32 v15, v47, v15
	v_exp_f32_e32 v51, v51
	v_sub_f32_e32 v52, v56, v8
	v_add_f32_e32 v15, v48, v15
	v_exp_f32_e32 v52, v52
	v_sub_f32_e32 v53, v57, v8
	v_add_f32_e32 v15, v49, v15
	v_exp_f32_e32 v53, v53
	v_sub_f32_e32 v54, v58, v8
	v_add_f32_e32 v15, v50, v15
	v_exp_f32_e32 v54, v54
	v_sub_f32_e32 v55, v59, v8
	v_add_f32_e32 v15, v51, v15
	v_exp_f32_e32 v55, v55
	v_sub_f32_e32 v56, v68, v8
	v_add_f32_e32 v15, v52, v15
	v_exp_f32_e32 v56, v56
	v_sub_f32_e32 v57, v69, v8
	v_add_f32_e32 v15, v53, v15
	v_exp_f32_e32 v57, v57
	v_sub_f32_e32 v58, v70, v8
	v_add_f32_e32 v15, v54, v15
	v_exp_f32_e32 v58, v58
	v_sub_f32_e32 v59, v71, v8
	v_add_f32_e32 v15, v55, v15
	v_exp_f32_e32 v59, v59
	v_sub_f32_e32 v60, v64, v8
	v_add_f32_e32 v15, v56, v15
	v_exp_f32_e32 v60, v60
	v_sub_f32_e32 v61, v65, v8
	v_add_f32_e32 v15, v57, v15
	v_exp_f32_e32 v61, v61
	v_sub_f32_e32 v62, v66, v8
	v_add_f32_e32 v15, v58, v15
	v_exp_f32_e32 v62, v62
	v_sub_f32_e32 v63, v67, v8
	v_add_f32_e32 v15, v59, v15
	v_exp_f32_e32 v63, v63
	v_sub_f32_e32 v64, v76, v8
	v_add_f32_e32 v15, v60, v15
	v_exp_f32_e32 v64, v64
	v_sub_f32_e32 v65, v77, v8
	v_add_f32_e32 v15, v61, v15
	v_exp_f32_e32 v65, v65
	v_sub_f32_e32 v66, v78, v8
	v_add_f32_e32 v15, v62, v15
	v_exp_f32_e32 v66, v66
	v_sub_f32_e32 v67, v79, v8
	v_add_f32_e32 v15, v63, v15
	v_exp_f32_e32 v67, v67
	v_sub_f32_e32 v68, v72, v8
	v_add_f32_e32 v15, v64, v15
	v_exp_f32_e32 v68, v68
	v_sub_f32_e32 v69, v73, v8
	v_add_f32_e32 v15, v65, v15
	v_exp_f32_e32 v69, v69
	v_sub_f32_e32 v70, v74, v8
	v_add_f32_e32 v15, v66, v15
	v_exp_f32_e32 v70, v70
	v_sub_f32_e32 v71, v75, v8
	v_add_f32_e32 v15, v67, v15
	v_exp_f32_e32 v71, v71
	v_sub_f32_e32 v72, v120, v8
	v_add_f32_e32 v15, v68, v15
	v_exp_f32_e32 v72, v72
	v_sub_f32_e32 v73, v121, v8
	v_add_f32_e32 v15, v69, v15
	v_exp_f32_e32 v73, v73
	v_sub_f32_e32 v74, v122, v8
	v_add_f32_e32 v15, v70, v15
	v_exp_f32_e32 v74, v74
	v_sub_f32_e32 v75, v123, v8
	v_add_f32_e32 v15, v71, v15
	v_exp_f32_e32 v75, v75
	v_sub_f32_e32 v76, v100, v8
	v_add_f32_e32 v15, v72, v15
	v_exp_f32_e32 v76, v76
	v_sub_f32_e32 v77, v101, v8
	v_add_f32_e32 v15, v73, v15
	v_exp_f32_e32 v77, v77
	v_sub_f32_e32 v78, v102, v8
	v_add_f32_e32 v15, v74, v15
	v_exp_f32_e32 v78, v78
	v_sub_f32_e32 v79, v103, v8
	v_add_f32_e32 v15, v75, v15
	v_exp_f32_e32 v79, v79
	v_sub_f32_e32 v4, v4, v8
	v_add_f32_e32 v15, v76, v15
	v_exp_f32_e32 v100, v4
	v_sub_f32_e32 v4, v5, v8
	v_add_f32_e32 v15, v77, v15
	v_exp_f32_e32 v101, v4
	v_sub_f32_e32 v4, v6, v8
	v_add_f32_e32 v15, v78, v15
	v_exp_f32_e32 v102, v4
	v_sub_f32_e32 v4, v7, v8
	v_add_f32_e32 v15, v79, v15
	v_exp_f32_e32 v103, v4
	v_sub_f32_e32 v0, v0, v8
	v_add_f32_e32 v4, v100, v15
	v_exp_f32_e32 v120, v0
	v_sub_f32_e32 v0, v1, v8
	v_add_f32_e32 v4, v101, v4
	v_exp_f32_e32 v121, v0
	v_sub_f32_e32 v0, v2, v8
	v_add_f32_e32 v4, v102, v4
	v_exp_f32_e32 v122, v0
	v_sub_f32_e32 v0, v3, v8
	v_add_f32_e32 v4, v103, v4
	v_exp_f32_e32 v123, v0
	v_add_f32_e32 v0, v120, v4
	v_add_f32_e32 v0, v121, v0
	v_add_f32_e32 v0, v122, v0
	v_add_f32_e32 v0, v123, v0
	ds_bpermute_b32 v1, v13, v0
	s_barrier
	s_waitcnt vmcnt(0) lgkmcnt(0)
	ds_write_b128 v142, v[16:19]
	ds_write_b128 v144, v[20:23]
	ds_write_b128 v146, v[28:31]
	ds_write_b128 v148, v[80:83]
	ds_write_b128 v150, v[84:87]
	ds_write_b128 v152, v[88:91]
	ds_write_b128 v154, v[92:95]
	ds_write_b128 v156, v[96:99]
	ds_write_b128 v158, v[104:107]
	ds_write_b128 v160, v[108:111]
	ds_write_b128 v162, v[112:115]
	ds_write_b128 v164, v[116:119]
	ds_write_b128 v166, v[124:127]
	ds_write_b128 v168, v[128:131]
	ds_write_b128 v170, v[132:135]
	ds_write_b128 v172, v[136:139]
	s_waitcnt lgkmcnt(0)
	v_add_f32_e32 v0, v0, v1
	ds_bpermute_b32 v1, v14, v0
	s_barrier
	s_waitcnt lgkmcnt(0)
	v_cvt_pk_bf16_f32 v2, v24, v25
	v_add_f32_e32 v145, v0, v1
	v_rcp_f32_e32 v16, v145
	v_lshl_add_u64 v[18:19], s[0:1], 0, v[140:141]
	v_lshl_add_u64 v[18:19], v[18:19], 0, s[82:83]
	v_lshl_add_u64 v[18:19], v[18:19], 0, v[192:193]
	s_mov_b64 s[0:1], 0x11e00000
	v_cvt_pk_bf16_f32 v0, v9, v10
	v_cvt_pk_bf16_f32 v1, v11, v12
	v_cvt_pk_bf16_f32 v3, v26, v27
	v_cvt_pk_bf16_f32 v4, v32, v33
	v_cvt_pk_bf16_f32 v5, v34, v35
	v_cvt_pk_bf16_f32 v6, v36, v37
	v_cvt_pk_bf16_f32 v7, v38, v39
	v_cvt_pk_bf16_f32 v8, v40, v41
	v_cvt_pk_bf16_f32 v9, v42, v43
	v_cvt_pk_bf16_f32 v10, v44, v45
	v_cvt_pk_bf16_f32 v11, v46, v47
	v_cvt_pk_bf16_f32 v12, v48, v49
	v_cvt_pk_bf16_f32 v13, v50, v51
	v_cvt_pk_bf16_f32 v14, v52, v53
	v_cvt_pk_bf16_f32 v15, v54, v55
	v_cvt_pk_bf16_f32 v24, v56, v57
	v_cvt_pk_bf16_f32 v25, v58, v59
	v_cvt_pk_bf16_f32 v26, v60, v61
	v_cvt_pk_bf16_f32 v27, v62, v63
	v_cvt_pk_bf16_f32 v32, v64, v65
	v_cvt_pk_bf16_f32 v33, v66, v67
	v_cvt_pk_bf16_f32 v34, v68, v69
	v_cvt_pk_bf16_f32 v35, v70, v71
	v_cvt_pk_bf16_f32 v36, v72, v73
	v_cvt_pk_bf16_f32 v37, v74, v75
	v_cvt_pk_bf16_f32 v38, v76, v77
	v_cvt_pk_bf16_f32 v39, v78, v79
	v_cvt_pk_bf16_f32 v40, v100, v101
	v_cvt_pk_bf16_f32 v41, v102, v103
	v_cvt_pk_bf16_f32 v42, v120, v121
	v_cvt_pk_bf16_f32 v43, v122, v123
	v_lshl_add_u64 v[18:19], v[18:19], 0, s[0:1]
	v_mov_b32_e32 v17, v16
	v_add3_u32 v20, v143, v192, 0
	s_mov_b32 s0, -2
	ds_read_b64 v[104:105], v20
	ds_read_b64 v[106:107], v20 offset:32
	ds_read_b64 v[108:109], v20 offset:64
	ds_read_b64 v[110:111], v20 offset:96
	ds_read_b64 v[112:113], v20 offset:128
	ds_read_b64 v[114:115], v20 offset:160
	ds_read_b64 v[116:117], v20 offset:192
	ds_read_b64 v[118:119], v20 offset:224
	ds_read_b64 v[120:121], v20 offset:256
	ds_read_b64 v[122:123], v20 offset:288
	ds_read_b64 v[124:125], v20 offset:320
	ds_read_b64 v[126:127], v20 offset:352
	ds_read_b64 v[128:129], v20 offset:384
	ds_read_b64 v[130:131], v20 offset:416
	ds_read_b64 v[132:133], v20 offset:448
	ds_read_b64 v[134:135], v20 offset:480
	v_add_u32_e32 v20, 0x2100, v20
	s_mov_b32 s0, 0

.LBB0_958:
	v_lshlrev_b64 v[24:25], 11, v[48:49]
	v_lshl_add_u64 v[24:25], s[30:31], 0, v[24:25]
	v_lshl_add_u64 v[20:21], v[20:21], 1, v[24:25]
	s_andn2_b64 vcc, exec, s[20:21]
	s_mov_b64 s[20:21], 0xb800000
	v_lshl_add_u64 v[20:21], v[20:21], 0, s[20:21]
	s_cbranch_vccnz .LBB0_960
	s_waitcnt vmcnt(0)
	global_load_dwordx2 v[2:3], v[20:21], off
	global_load_dwordx2 v[96:97], v[20:21], off offset:32
	global_load_dwordx2 v[98:99], v[20:21], off offset:64
	global_load_dwordx2 v[100:101], v[20:21], off offset:96
	s_waitcnt vmcnt(0) lgkmcnt(0)
	v_lshlrev_b32_e32 v0, 16, v2
	v_and_b32_e32 v1, 0xffff0000, v2
	v_lshlrev_b32_e32 v2, 16, v3
	v_and_b32_e32 v3, 0xffff0000, v3

.LBB0_962:
	v_mov_b32_e32 v2, v96
	v_mov_b32_e32 v3, v97
	v_lshlrev_b32_e32 v0, 16, v2
	v_and_b32_e32 v1, 0xffff0000, v2
	v_lshlrev_b32_e32 v2, 16, v3
	v_and_b32_e32 v3, 0xffff0000, v3
	s_branch .Lm8_a

.Lm8_a:
	v_pk_add_f32 v[2:3], v[14:15], v[2:3]
	v_pk_add_f32 v[0:1], v[12:13], v[0:1]
	v_cvt_pk_bf16_f32 v13, v2, v3
	v_cvt_pk_bf16_f32 v12, v0, v1
	s_and_b64 vcc, exec, s[0:1]
	global_store_dwordx2 v[20:21], v[12:13], off offset:32
	s_cbranch_vccnz .LBB0_972
	global_load_dwordx4 v[0:3], v[22:23], off offset:128
	s_cbranch_execnz .LBB0_966
.LBB0_965:
	v_mov_b32_e32 v2, v98
	v_mov_b32_e32 v3, v99
	v_lshlrev_b32_e32 v0, 16, v2
	v_and_b32_e32 v1, 0xffff0000, v2
	v_lshlrev_b32_e32 v2, 16, v3
	v_and_b32_e32 v3, 0xffff0000, v3
	s_branch .Lm8_b

.Lm8_b:
	v_pk_add_f32 v[2:3], v[10:11], v[2:3]
	v_pk_add_f32 v[0:1], v[8:9], v[0:1]
	v_cvt_pk_bf16_f32 v9, v2, v3
	v_cvt_pk_bf16_f32 v8, v0, v1
	s_and_b64 vcc, exec, s[0:1]
	global_store_dwordx2 v[20:21], v[8:9], off offset:64
	s_cbranch_vccnz .LBB0_973
	global_load_dwordx4 v[0:3], v[22:23], off offset:192
	s_cbranch_execnz .LBB0_969
.LBB0_968:
	v_mov_b32_e32 v2, v100
	v_mov_b32_e32 v3, v101
	v_lshlrev_b32_e32 v0, 16, v2
	v_and_b32_e32 v1, 0xffff0000, v2
	v_lshlrev_b32_e32 v2, 16, v3
	v_and_b32_e32 v3, 0xffff0000, v3
